# v22 + S5 pass B output stores widened: lane pairs trade halves (DPP quad_perm + v_perm), two dword stores per block instead of four 2-byte stores
# baseline (speedup 1.0000x reference)
; #define LAS __attribute__((address_space(3)))
; template <bool FULL>
; __device__ __forceinline__ void s5_pass(const Params& P, LAS unsigned char* lds, int bx, int tid_in) {
;     int tid = tid_in; asm volatile("" : "+v"(tid)); const int lane = tid & 63, wave = __builtin_amdgcn_readfirstlane(tid >> 6);
;     unsigned char* ws = P.ws;
;     const bf16_t* U = (const bf16_t*)(ws + WS_Q); bf16_t* YG = (bf16_t*)(ws + WS_V);
;     const float* AB = (const float*)(ws + WS_MISC + MISC_AB); const bf16_t* BBT = (const bf16_t*)(ws + WS_MISC + MISC_BBT); const bf16_t* CMT = (const bf16_t*)(ws + WS_MISC + MISC_CMT);
;     f32x4* SEG = (f32x4*)(ws + WS_MISC + MISC_SEG);
;     LAS unsigned char* hl = lds + wave * (32 * HROW);
;     const int r32 = lane & 31, hi = lane >> 5, l16 = lane & 15, kg = lane >> 4;
;     for (int task = bx * NWAVES + wave; task < 4096; task += NWAVES * (int)gridDim.x) {
;         const int g = task & 127, bp = (task >> 7) & 3, seg = task >> 9;
;         if (!FULL && seg == 7) continue;
;         const float ar0 = AB[(g * 64 + r32) * 2], ai0 = AB[(g * 64 + r32) * 2 + 1], ar1 = AB[(g * 64 + 32 + r32) * 2], ai1 = AB[(g * 64 + 32 + r32) * 2 + 1];
;         bf16x8 bfr[4], cfr[4];
; #pragma unroll
;         for (int j = 0; j < 4; ++j) { bfr[j] = *(const bf16x8*)(BBT + ((g * 4 + j) * 32 + r32) * 16 + 8 * hi); if (FULL) cfr[j] = *(const bf16x8*)(CMT + (g * 16 + l16) * 128 + 32 * j + 8 * kg); }
;         bf16x8 dh, dl;
;         if (FULL) { const float d = P.in[20][g * 16 + l16]; const unsigned h16 = f2bf(d); const unsigned l16b = f2bf(d - __builtin_bit_cast(float, h16 << 16));
; #pragma unroll
;           for (int i = 0; i < 8; ++i) { const bool on = (kg < 2) && (8 * kg + i == l16); dh[i] = on ? (short)h16 : (short)0; dl[i] = on ? (short)l16b : (short)0; } }
;         const int m = r32, bsel = (m >> 2) & 1, tok = (m & 3) + 4 * (m >> 3);
;         const int tbeg = seg * S5_SEGLEN;
;         const bf16_t* u32p = U + ((size_t)(bp + 4 * bsel) * SEQ + tbeg + tok) * BR + g * 16 + 8 * hi;
;         const bf16_t* u16p = U + ((size_t)bp * SEQ + tbeg + l16) * BR + g * 16 + 8 * (kg & 1);
;         bf16_t* yp = YG + ((size_t)bp * SEQ + tbeg + 4 * kg) * BR + g * 16 + l16;
;         float h0r = 0.f, h0i = 0.f, h1r = 0.f, h1i = 0.f;
.LBB0_416:
	s_or_b64 exec, exec, s[4:5]
	v_mov_b32_e32 v0, v215
	s_barrier
	s_nop 0
	v_readfirstlane_b32 s5, v0
	s_ashr_i32 s4, s5, 6
	s_add_i32 s52, s4, s33
	s_cmpk_gt_i32 s52, 0xfff
	s_cbranch_scc1 .LBB0_427
	v_and_b32_e32 v1, 63, v0
	v_mov_b32_e32 v127, 0
	v_bfe_u32 v3, v0, 4, 2
	s_mulk_i32 s4, 0x2200
	v_lshlrev_b32_e32 v6, 4, v1
	v_mov_b32_e32 v7, v127
	s_lshr_b32 s40, s5, 6
	s_add_i32 s8, s4, 0
	v_lshlrev_b32_e32 v9, 3, v3
	v_lshl_add_u64 v[6:7], s[30:31], 0, v[6:7]
	s_mov_b64 s[4:5], 0x1ec00000
	v_and_b32_e32 v124, 15, v0
	v_bfe_u32 v5, v0, 5, 1
	v_lshl_add_u64 v[138:139], v[6:7], 0, s[4:5]
	v_or_b32_e32 v6, 1, v9
	v_lshlrev_b32_e32 v126, 4, v5
	v_cmp_eq_u32_e64 s[10:11], v6, v124
	v_or_b32_e32 v6, 2, v9
	v_lshl_add_u64 v[128:129], s[16:17], 0, v[126:127]
	v_and_b32_e32 v126, 48, v0
	v_cmp_eq_u32_e64 s[12:13], v6, v124
	v_or_b32_e32 v6, 3, v9
	v_lshl_add_u64 v[130:131], s[14:15], 0, v[126:127]
	v_cmp_eq_u32_e64 s[14:15], v6, v124
	v_or_b32_e32 v6, 4, v9
	v_lshlrev_b32_e32 v134, 2, v3
	v_add_u32_e32 v3, s8, v126
	v_cmp_eq_u32_e64 s[16:17], v6, v124
	v_or_b32_e32 v6, 5, v9
	v_lshlrev_b32_e32 v126, 1, v124
	v_lshrrev_b32_e32 v10, 1, v0
	v_cmp_eq_u32_e64 s[18:19], v6, v124
	v_or_b32_e32 v6, 6, v9
	v_lshl_add_u64 v[140:141], s[30:31], 0, v[126:127]
	v_and_b32_e32 v126, 16, v0
	v_and_b32_e32 v125, 31, v0
	v_and_b32_e32 v4, 3, v0
	v_cmp_eq_u32_e64 s[20:21], v6, v124
	v_or_b32_e32 v6, 7, v9
	v_lshl_add_u64 v[142:143], s[30:31], 0, v[126:127]
	v_and_b32_e32 v126, 16, v10
	v_lshlrev_b32_e32 v2, 3, v5
	v_lshlrev_b32_e32 v8, 7, v124
	v_cmp_gt_u32_e32 vcc, 32, v1
	v_and_b32_e32 v135, 4, v0
	v_and_or_b32 v132, v10, 12, v4
	v_and_b32_e32 v4, 8, v9
	v_cmp_lt_u32_e64 s[4:5], 31, v1
	v_lshl_add_u32 v1, v125, 2, s8
	v_cmp_eq_u32_e64 s[8:9], v9, v124
	v_cmp_eq_u32_e64 s[22:23], v6, v124
	v_mul_u32_u24_e32 v5, 0x1100, v5
	v_mul_u32_u24_e32 v9, 0x110, v124
	v_lshl_add_u64 v[6:7], s[30:31], 0, v[126:127]
	s_mov_b64 s[42:43], 0x6810000
	v_lshlrev_b32_e32 v0, 12, v0
	s_mov_b32 s41, 0
	v_lshlrev_b32_e32 v133, 1, v125
	s_and_b64 s[8:9], vcc, s[8:9]
	s_and_b64 s[10:11], vcc, s[10:11]
	s_and_b64 s[12:13], vcc, s[12:13]
	s_and_b64 s[14:15], vcc, s[14:15]
	s_and_b64 s[16:17], vcc, s[16:17]
	s_and_b64 s[18:19], vcc, s[18:19]
	s_and_b64 s[20:21], vcc, s[20:21]
	s_and_b64 s[22:23], vcc, s[22:23]
	s_add_i32 s33, s33, s40
	s_mul_i32 s71, s40, 9216
	s_add_i32 s71, s71, 69632
	s_add_i32 s73, s71, 8192
	s_mov_b32 s77, 0
	s_mov_b32 s82, 0xffff0000
	s_mov_b32 s83, -1
	s_add_u32 s78, s30, 0x16800000
	s_addc_u32 s79, s31, 0
	s_add_u32 s80, s30, 0x1a800000
	s_addc_u32 s81, s31, 0
	v_and_b32_e32 v186, 63, v215
	v_lshlrev_b32_e32 v184, 4, v186
	v_and_b32_e32 v185, 3, v124
	v_lshrrev_b32_e32 v186, 2, v124
	v_lshl_add_u32 v185, v186, 3, v185
	v_lshlrev_b32_e32 v185, 4, v185
	v_and_b32_e32 v186, 16, v215
	v_lshl_add_u32 v185, v186, 5, v185
	v_and_b32_e32 v186, 7, v215
	v_mov_b32_e32 v214, 0x23000
	v_lshl_add_u32 v186, v186, 4, v214
	v_mov_b32_e32 v216, 0
	v_mov_b32_e32 v217, 0
	v_mov_b32_e32 v218, 0
	v_mov_b32_e32 v219, 0
	ds_write_b128 v186, v[216:219]
	s_waitcnt lgkmcnt(0)
	s_mov_b32 s84, 0x55555555
	s_mov_b32 s85, 0x55555555
	v_mov_b32_e32 v231, 0x01000504
	v_mov_b32_e32 v232, 0x03020706
	v_mov_b32_e32 v233, 0x05040100
	v_mov_b32_e32 v234, 0x07060302
	v_cndmask_b32_e64 v231, v231, v233, s[84:85]
	v_cndmask_b32_e64 v232, v232, v234, s[84:85]
	v_lshl_add_u64 v[144:145], v[6:7], 0, s[42:43]
	v_and_b32_e32 v172, 0x4000, v0
	v_lshlrev_b32_e32 v173, 1, v8
	s_movk_i32 s53, 0x7fff
	v_lshlrev_b32_e32 v146, 1, v2
	v_lshlrev_b32_e32 v148, 1, v4
	s_brev_b32 s54, 32
	s_mov_b32 s55, 0x5040100
	v_add_u32_e32 v174, v1, v5
	v_add_u32_e32 v226, 0x400, v174
	v_add_u32_e32 v227, 0x800, v174
	v_add_u32_e32 v228, 0xa00, v174
	v_add_u32_e32 v229, 0xc00, v174
	v_add_u32_e32 v230, 0xe00, v174
	v_add_u32_e32 v175, v3, v9
	s_mov_b32 s56, 0x16800000
	s_mov_b32 s57, 0x16801000
	s_mov_b32 s58, 0x16802000
	s_mov_b32 s59, 0x16803000
	s_mov_b32 s60, 0x1a800000
	s_mov_b32 s61, 0x1a801000
	s_mov_b64 s[42:43], 0x10000
	s_branch .LBB0_419

; __device__ __forceinline__ unsigned f2bf(float f) { unsigned u = __builtin_bit_cast(unsigned, f); return (u + 0x7fffu + ((u >> 16) & 1u)) >> 16; }
; template <bool FULL>
; __device__ __forceinline__ void s5_pass(const Params& P, LAS unsigned char* lds, int bx, int tid_in) {
;     ...
;         if (FULL) { const float d = P.in[20][g * 16 + l16]; const unsigned h16 = f2bf(d); const unsigned l16b = f2bf(d - __builtin_bit_cast(float, h16 << 16));
; #pragma unroll
;           for (int i = 0; i < 8; ++i) { const bool on = (kg < 2) && (8 * kg + i == l16); dh[i] = on ? (short)h16 : (short)0; dl[i] = on ? (short)l16b : (short)0; } }
;         const int m = r32, bsel = (m >> 2) & 1, tok = (m & 3) + 4 * (m >> 3);
;         const int tbeg = seg * S5_SEGLEN;
;         const bf16_t* u32p = U + ((size_t)(bp + 4 * bsel) * SEQ + tbeg + tok) * BR + g * 16 + 8 * hi;
;         const bf16_t* u16p = U + ((size_t)bp * SEQ + tbeg + l16) * BR + g * 16 + 8 * (kg & 1);
;         bf16_t* yp = YG + ((size_t)bp * SEQ + tbeg + 4 * kg) * BR + g * 16 + l16;
.LBB0_423:
	s_bfe_u32 s63, s52, 0x20007
	s_and_b32 s50, s52, 0xfffffe00
	s_and_b32 s40, s33, 0x7f
	s_ashr_i32 s51, s50, 31
	s_lshl_b32 s64, s63, 12
	s_lshl_b32 s40, s40, 5
	v_mov_b32_e32 v3, s51
	v_or_b32_e32 v2, s50, v132
	v_add_u32_e32 v126, s64, v172
	v_or_b32_e32 v4, s63, v135
	s_add_u32 s65, s50, s64
	v_lshl_add_u64 v[2:3], v[2:3], 0, v[126:127]
	v_lshlrev_b32_e32 v126, 12, v4
	s_addc_u32 s66, s51, 0
	v_lshl_add_u64 v[4:5], v[126:127], 0, s[50:51]
	v_mov_b32_e32 v1, s66
	v_or_b32_e32 v0, s65, v124
	v_or_b32_e32 v4, v4, v132
	v_lshlrev_b64 v[0:1], 12, v[0:1]
	v_lshlrev_b64 v[4:5], 12, v[4:5]
	v_lshl_add_u64 v[4:5], s[34:35], 0, v[4:5]
	s_lshl_b32 s50, s62, 1
	s_mov_b32 s51, s41
	v_lshl_add_u64 v[6:7], s[34:35], 0, v[0:1]
	v_lshl_add_u64 v[4:5], v[4:5], 0, s[50:51]
	v_mov_b32_e32 v147, v127
	v_lshl_add_u64 v[6:7], v[6:7], 0, s[50:51]
	v_mov_b32_e32 v149, v127
	v_lshl_add_u64 v[4:5], v[4:5], 0, v[146:147]
	v_lshl_add_u64 v[6:7], v[6:7], 0, v[148:149]
	v_lshlrev_b64 v[2:3], 12, v[2:3]
	s_waitcnt vmcnt(0)
	v_bfe_u32 v4, v8, 16, 1
	v_add3_u32 v4, v8, v4, s53
	v_and_b32_e32 v6, 0xffff0000, v4
	v_sub_f32_e32 v6, v8, v6
	v_lshrrev_b32_e32 v5, 16, v4
	v_bfe_u32 v15, v6, 16, 1
	v_or_b32_e32 v4, s65, v134
	v_cndmask_b32_e64 v7, 0, v5, s[8:9]
	v_cndmask_b32_e64 v8, 0, v5, s[10:11]
	v_cndmask_b32_e64 v9, 0, v5, s[12:13]
	v_cndmask_b32_e64 v10, 0, v5, s[14:15]
	v_cndmask_b32_e64 v11, 0, v5, s[16:17]
	v_cndmask_b32_e64 v12, 0, v5, s[18:19]
	v_cndmask_b32_e64 v13, 0, v5, s[20:21]
	v_cndmask_b32_e64 v14, 0, v5, s[22:23]
	v_mov_b32_e32 v5, s66
	v_lshl_add_u64 v[166:167], v[144:145], 0, v[2:3]
	v_add3_u32 v2, v6, v15, s53
	v_lshlrev_b64 v[4:5], 12, v[4:5]
	v_lshl_add_u64 v[170:171], v[142:143], 0, v[0:1]
	v_lshrrev_b32_e32 v0, 16, v2
	v_perm_b32 v96, v8, v7, s55
	v_lshl_add_u64 v[168:169], v[140:141], 0, v[4:5]
	v_cndmask_b32_e64 v1, 0, v0, s[8:9]
	v_cndmask_b32_e64 v2, 0, v0, s[10:11]
	v_cndmask_b32_e64 v3, 0, v0, s[12:13]
	v_cndmask_b32_e64 v4, 0, v0, s[14:15]
	v_cndmask_b32_e64 v5, 0, v0, s[16:17]
	v_cndmask_b32_e64 v6, 0, v0, s[18:19]
	v_cndmask_b32_e64 v7, 0, v0, s[20:21]
	v_cndmask_b32_e64 v0, 0, v0, s[22:23]
	s_mov_b32 s62, 0
	v_perm_b32 v99, v14, v13, s55
	v_perm_b32 v98, v12, v11, s55
	v_perm_b32 v97, v10, v9, s55
	v_perm_b32 v103, v0, v7, s55
	v_perm_b32 v102, v6, v5, s55
	v_perm_b32 v101, v4, v3, s55
	v_perm_b32 v100, v2, v1, s55
	v_mov_b32_e32 v156, v32
	v_mov_b32_e32 v157, v33
	v_mov_b32_e32 v158, v52
	v_mov_b32_e32 v159, v53
	v_xor_b32_e32 v154, 0x80000000, v151
	v_xor_b32_e32 v155, 0x80000000, v153
	v_lshl_add_u64 v[188:189], v[166:167], 0, s[40:41]
	v_lshl_add_u64 v[188:189], v[188:189], 0, s[82:83]
	s_add_i32 m0, s71, 0
	s_nop 0
	global_load_lds_dwordx4 v[188:189], off
	v_lshl_add_u64 v[188:189], v[188:189], 0, s[42:43]
	s_add_i32 m0, s71, 1024
	s_nop 0
	global_load_lds_dwordx4 v[188:189], off
	v_lshl_add_u64 v[188:189], v[188:189], 0, s[42:43]
	s_add_i32 m0, s71, 2048
	s_nop 0
	global_load_lds_dwordx4 v[188:189], off
	v_lshl_add_u64 v[188:189], v[188:189], 0, s[42:43]
	s_add_i32 m0, s71, 3072
	s_nop 0
	global_load_lds_dwordx4 v[188:189], off
	v_lshl_add_u64 v[188:189], v[188:189], 0, s[42:43]
	s_add_i32 m0, s71, 4096
	s_nop 0
	global_load_lds_dwordx4 v[188:189], off
	v_lshl_add_u64 v[188:189], v[188:189], 0, s[42:43]
	s_add_i32 m0, s71, 5120
	s_nop 0
	global_load_lds_dwordx4 v[188:189], off
	v_lshl_add_u64 v[188:189], v[188:189], 0, s[42:43]
	s_add_i32 m0, s71, 6144
	s_nop 0
	global_load_lds_dwordx4 v[188:189], off
	v_lshl_add_u64 v[188:189], v[188:189], 0, s[42:43]
	s_add_i32 m0, s71, 7168
	s_nop 0
	global_load_lds_dwordx4 v[188:189], off
	v_lshl_add_u64 v[188:189], v[188:189], 0, s[42:43]
	s_add_i32 s72, s71, 1024
	v_or_b32_e32 v224, s65, v134
	v_lshlrev_b32_e32 v224, 12, v224
	v_lshl_add_u32 v224, v124, 1, v224
	v_add_u32_e32 v224, s40, v224
	v_add_u32_e32 v225, 0x3000, v224
	v_add_u32_e32 v224, 0x1000, v224
	v_subrev_u32_e32 v225, 2, v225
	v_cndmask_b32_e64 v224, v225, v224, s[84:85]
	s_movk_i32 s75, 32
	v_add_u32_e32 v186, s71, v184
	v_add_u32_e32 v187, s71, v185
	v_cndmask_b32_e64 v187, v187, v214, s[4:5]
	s_waitcnt vmcnt(0)
	ds_read_b128 v[104:107], v186
	ds_read_b128 v[108:111], v187
	ds_read_b128 v[112:115], v187 offset:64
	s_mov_b32 m0, s71
	s_waitcnt lgkmcnt(0)
	global_load_lds_dwordx4 v[188:189], off
	v_lshl_add_u64 v[188:189], v[188:189], 0, s[42:43]
	s_mov_b32 s74, 9
; #define LAS __attribute__((address_space(3)))
; __device__ __forceinline__ unsigned cvtpk_s(float lo, float hi) { f32x2_t v = {lo, hi}; bf16x2_t b = __builtin_convertvector(v, bf16x2_t); return __builtin_bit_cast(unsigned, b); }
; template <bool FULL>
; __device__ __forceinline__ void s5_pass(const Params& P, LAS unsigned char* lds, int bx, int tid_in) {
;     ...
;         for (int t0 = 0; t0 < S5_SEGLEN; t0 += 16) {
;             const bf16x8 ca = ua; bf16x8 cb0, cb1; if (FULL) { cb0 = ub0; cb1 = ub1; }
;             if (t0 + 16 < S5_SEGLEN) { const size_t o = (size_t)(t0 + 16) * BR; ua = *(const bf16x8*)(u32p + o); if (FULL) { ub0 = *(const bf16x8*)(u16p + o); ub1 = *(const bf16x8*)(u16p + o + (size_t)4 * SEQ * BR); } }
;             if (FULL && kg >= 2) { cb0 = (bf16x8){0, 0, 0, 0, 0, 0, 0, 0}; cb1 = cb0; }
;             f32x16 acc[4];
; #pragma unroll
;             for (int j = 0; j < 4; ++j) {
; #pragma unroll
;                 for (int r = 0; r < 16; ++r) acc[j][r] = 0.f;
;                 acc[j] = __builtin_amdgcn_mfma_f32_32x32x16_bf16(ca, bfr[j], acc[j], 0, 0, 0); }
; #pragma unroll
;             for (int r = 0; r < 16; ++r) {
;                 const float n0r = ar0 * h0r - ai0 * h0i + acc[0][r], n0i = ar0 * h0i + ai0 * h0r + acc[2][r];
;                 const float n1r = ar1 * h1r - ai1 * h1i + acc[1][r], n1i = ar1 * h1i + ai1 * h1r + acc[3][r];
;                 h0r = n0r; h0i = n0i; h1r = n1r; h1i = n1i;
;                 if (FULL) { *(LAS unsigned*)(hl + (16 * hi + r) * HROW + r32 * 4) = cvtpk_s(n0r, n0i);
;                     *(LAS unsigned*)(hl + (16 * hi + r) * HROW + (32 + r32) * 4) = cvtpk_s(n1r, n1i); }
;             }
.Ls5b_step:
	v_mfma_f32_32x32x16_bf16 v[0:15], v[104:107], v[64:67], 0
	v_mfma_f32_32x32x16_bf16 v[16:31], v[104:107], v[80:83], 0
	v_mfma_f32_32x32x16_bf16 v[32:47], v[104:107], v[68:71], 0
	v_mfma_f32_32x32x16_bf16 v[48:63], v[104:107], v[84:87], 0
	s_cmp_lt_u32 s74, 31
	s_cselect_b32 s76, 0x10000, 0
	s_cmp_lt_u32 s74, 32
	s_cselect_b32 m0, s72, s73
	s_add_i32 s74, s74, 1
	v_add_u32_e32 v186, s72, v184
	v_add_u32_e32 v187, s72, v185
	s_add_i32 s72, s72, 1024
	s_cmp_eq_u32 s72, s73
	s_cselect_b32 s72, s71, s72
	v_cndmask_b32_e64 v187, v187, v214, s[4:5]
	v_fmac_f32_e32 v0, v150, v156
	v_fmac_f32_e32 v16, v150, v157
	v_fmac_f32_e32 v32, v152, v158
	v_fmac_f32_e32 v48, v152, v159
	v_fmac_f32_e32 v0, v154, v157
	v_fmac_f32_e32 v16, v151, v156
	v_fmac_f32_e32 v32, v155, v159
	v_fmac_f32_e32 v48, v153, v158
	v_fmac_f32_e32 v1, v150, v0
	v_fmac_f32_e32 v17, v150, v16
	v_fmac_f32_e32 v33, v152, v32
	v_fmac_f32_e32 v49, v152, v48
	v_fmac_f32_e32 v1, v154, v16
	v_fmac_f32_e32 v17, v151, v0
	v_fmac_f32_e32 v33, v155, v48
	v_fmac_f32_e32 v49, v153, v32
	v_cvt_pk_bf16_f32 v160, v0, v16
	v_cvt_pk_bf16_f32 v161, v32, v48
	ds_write2_b32 v174, v160, v161 offset0:0 offset1:32
	s_waitcnt vmcnt(63)
	ds_read_b128 v[104:107], v186
	v_fmac_f32_e32 v2, v150, v1
	v_fmac_f32_e32 v18, v150, v17
	v_fmac_f32_e32 v34, v152, v33
	v_fmac_f32_e32 v50, v152, v49
	v_fmac_f32_e32 v2, v154, v17
	v_fmac_f32_e32 v18, v151, v1
	v_fmac_f32_e32 v34, v155, v49
	v_fmac_f32_e32 v50, v153, v33
	v_cvt_pk_bf16_f32 v162, v1, v17
	v_cvt_pk_bf16_f32 v163, v33, v49
	ds_write2_b32 v174, v162, v163 offset0:68 offset1:100
	v_fmac_f32_e32 v3, v150, v2
	v_fmac_f32_e32 v19, v150, v18
	v_fmac_f32_e32 v35, v152, v34
	v_fmac_f32_e32 v51, v152, v50
	v_fmac_f32_e32 v3, v154, v18
	v_fmac_f32_e32 v19, v151, v2
	v_fmac_f32_e32 v35, v155, v50
	v_fmac_f32_e32 v51, v153, v34
	v_cvt_pk_bf16_f32 v160, v2, v18
	v_cvt_pk_bf16_f32 v161, v34, v50
	ds_write2_b32 v174, v160, v161 offset0:136 offset1:168
	v_fmac_f32_e32 v4, v150, v3
	v_fmac_f32_e32 v20, v150, v19
	v_fmac_f32_e32 v36, v152, v35
	v_fmac_f32_e32 v52, v152, v51
	v_fmac_f32_e32 v4, v154, v19
	v_fmac_f32_e32 v20, v151, v3
	v_fmac_f32_e32 v36, v155, v51
	v_fmac_f32_e32 v52, v153, v35
	v_cvt_pk_bf16_f32 v162, v3, v19
	v_cvt_pk_bf16_f32 v163, v35, v51
	ds_write2_b32 v174, v162, v163 offset0:204 offset1:236
	v_fmac_f32_e32 v5, v150, v4
	v_fmac_f32_e32 v21, v150, v20
	v_fmac_f32_e32 v37, v152, v36
	v_fmac_f32_e32 v53, v152, v52
	v_fmac_f32_e32 v5, v154, v20
	v_fmac_f32_e32 v21, v151, v4
	v_fmac_f32_e32 v37, v155, v52
	v_fmac_f32_e32 v53, v153, v36
	v_cvt_pk_bf16_f32 v160, v4, v20
	v_cvt_pk_bf16_f32 v161, v36, v52
	ds_write2_b32 v226, v160, v161 offset0:16 offset1:48
	v_fmac_f32_e32 v6, v150, v5
	v_fmac_f32_e32 v22, v150, v21
	v_fmac_f32_e32 v38, v152, v37
	v_fmac_f32_e32 v54, v152, v53
	v_fmac_f32_e32 v6, v154, v21
	v_fmac_f32_e32 v22, v151, v5
	v_fmac_f32_e32 v38, v155, v53
	v_fmac_f32_e32 v54, v153, v37
	v_cvt_pk_bf16_f32 v162, v5, v21
	v_cvt_pk_bf16_f32 v163, v37, v53
	ds_write2_b32 v226, v162, v163 offset0:84 offset1:116
	v_fmac_f32_e32 v7, v150, v6
	v_fmac_f32_e32 v23, v150, v22
	v_fmac_f32_e32 v39, v152, v38
	v_fmac_f32_e32 v55, v152, v54
	v_fmac_f32_e32 v7, v154, v22
	v_fmac_f32_e32 v23, v151, v6
	v_fmac_f32_e32 v39, v155, v54
	v_fmac_f32_e32 v55, v153, v38
	v_cvt_pk_bf16_f32 v160, v6, v22
	v_cvt_pk_bf16_f32 v161, v38, v54
	ds_write2_b32 v226, v160, v161 offset0:152 offset1:184
	v_fmac_f32_e32 v8, v150, v7
	v_fmac_f32_e32 v24, v150, v23
	v_fmac_f32_e32 v40, v152, v39
	v_fmac_f32_e32 v56, v152, v55
	v_fmac_f32_e32 v8, v154, v23
	v_fmac_f32_e32 v24, v151, v7
	v_fmac_f32_e32 v40, v155, v55
	v_fmac_f32_e32 v56, v153, v39
	v_cvt_pk_bf16_f32 v162, v7, v23
	v_cvt_pk_bf16_f32 v163, v39, v55
	ds_write2_b32 v226, v162, v163 offset0:220 offset1:252
	v_fmac_f32_e32 v9, v150, v8
	v_fmac_f32_e32 v25, v150, v24
	v_fmac_f32_e32 v41, v152, v40
	v_fmac_f32_e32 v57, v152, v56
	v_fmac_f32_e32 v9, v154, v24
	v_fmac_f32_e32 v25, v151, v8
	v_fmac_f32_e32 v41, v155, v56
	v_fmac_f32_e32 v57, v153, v40
	v_cvt_pk_bf16_f32 v160, v8, v24
	v_cvt_pk_bf16_f32 v161, v40, v56
	ds_write2_b32 v227, v160, v161 offset0:32 offset1:64
	v_fmac_f32_e32 v10, v150, v9
	v_fmac_f32_e32 v26, v150, v25
	v_fmac_f32_e32 v42, v152, v41
	v_fmac_f32_e32 v58, v152, v57
	v_fmac_f32_e32 v10, v154, v25
	v_fmac_f32_e32 v26, v151, v9
	v_fmac_f32_e32 v42, v155, v57
	v_fmac_f32_e32 v58, v153, v41
	v_cvt_pk_bf16_f32 v162, v9, v25
	v_cvt_pk_bf16_f32 v163, v41, v57
	ds_write2_b32 v227, v162, v163 offset0:100 offset1:132
	v_fmac_f32_e32 v11, v150, v10
	v_fmac_f32_e32 v27, v150, v26
	v_fmac_f32_e32 v43, v152, v42
	v_fmac_f32_e32 v59, v152, v58
	v_fmac_f32_e32 v11, v154, v26
	v_fmac_f32_e32 v27, v151, v10
	v_fmac_f32_e32 v43, v155, v58
	v_fmac_f32_e32 v59, v153, v42
	v_cvt_pk_bf16_f32 v160, v10, v26
	v_cvt_pk_bf16_f32 v161, v42, v58
	ds_write2_b32 v228, v160, v161 offset0:40 offset1:72
	v_fmac_f32_e32 v12, v150, v11
	v_fmac_f32_e32 v28, v150, v27
	v_fmac_f32_e32 v44, v152, v43
	v_fmac_f32_e32 v60, v152, v59
	v_fmac_f32_e32 v12, v154, v27
	v_fmac_f32_e32 v28, v151, v11
	v_fmac_f32_e32 v44, v155, v59
	v_fmac_f32_e32 v60, v153, v43
	v_cvt_pk_bf16_f32 v162, v11, v27
	v_cvt_pk_bf16_f32 v163, v43, v59
	ds_write2_b32 v228, v162, v163 offset0:108 offset1:140
	v_fmac_f32_e32 v13, v150, v12
	v_fmac_f32_e32 v29, v150, v28
	v_fmac_f32_e32 v45, v152, v44
	v_fmac_f32_e32 v61, v152, v60
	v_fmac_f32_e32 v13, v154, v28
	v_fmac_f32_e32 v29, v151, v12
	v_fmac_f32_e32 v45, v155, v60
	v_fmac_f32_e32 v61, v153, v44
	v_cvt_pk_bf16_f32 v160, v12, v28
	v_cvt_pk_bf16_f32 v161, v44, v60
	ds_write2_b32 v229, v160, v161 offset0:48 offset1:80
	v_fmac_f32_e32 v14, v150, v13
	v_fmac_f32_e32 v30, v150, v29
	v_fmac_f32_e32 v46, v152, v45
	v_fmac_f32_e32 v62, v152, v61
	v_fmac_f32_e32 v14, v154, v29
	v_fmac_f32_e32 v30, v151, v13
	v_fmac_f32_e32 v46, v155, v61
	v_fmac_f32_e32 v62, v153, v45
	v_cvt_pk_bf16_f32 v162, v13, v29
	v_cvt_pk_bf16_f32 v163, v45, v61
	ds_write2_b32 v229, v162, v163 offset0:116 offset1:148
	v_fmac_f32_e32 v15, v150, v14
	v_fmac_f32_e32 v31, v150, v30
	v_fmac_f32_e32 v47, v152, v46
	v_fmac_f32_e32 v63, v152, v62
	v_fmac_f32_e32 v15, v154, v30
	v_fmac_f32_e32 v31, v151, v14
	v_fmac_f32_e32 v47, v155, v62
	v_fmac_f32_e32 v63, v153, v46
	v_cvt_pk_bf16_f32 v160, v14, v30
	v_cvt_pk_bf16_f32 v161, v46, v62
	ds_write2_b32 v230, v160, v161 offset0:56 offset1:88
	v_cvt_pk_bf16_f32 v162, v15, v31
	v_cvt_pk_bf16_f32 v163, v47, v63
	ds_write2_b32 v230, v162, v163 offset0:124 offset1:156
	ds_read_b128 v[116:119], v175
	ds_read_b128 v[120:123], v175 offset:64
	ds_read_b128 v[176:179], v175 offset:128
	ds_read_b128 v[180:183], v175 offset:192
	ds_read_b128 v[190:193], v175 offset:4352
	ds_read_b128 v[194:197], v175 offset:4416
	ds_read_b128 v[198:201], v175 offset:4480
	ds_read_b128 v[202:205], v175 offset:4544
	v_mov_b32_e32 v156, v15
	v_mov_b32_e32 v157, v31
	v_mov_b32_e32 v158, v47
	v_mov_b32_e32 v159, v63
	s_waitcnt lgkmcnt(7)
; #define LAS __attribute__((address_space(3)))
; __device__ __forceinline__ float gelu_tanh(float y) { const float t = (-1.5957691216057308f * LOG2E) * (y + 0.044715f * y * y * y); return y * __builtin_amdgcn_rcpf(1.f + __builtin_amdgcn_exp2f(t)); }
; __device__ __forceinline__ unsigned cvtpk_s(float lo, float hi) { f32x2_t v = {lo, hi}; bf16x2_t b = __builtin_convertvector(v, bf16x2_t); return __builtin_bit_cast(unsigned, b); }
; template <bool FULL>
; __device__ __forceinline__ void s5_pass(const Params& P, LAS unsigned char* lds, int bx, int tid_in) {
;     ...
;             if (FULL) {
; #pragma unroll
;             for (int blk = 0; blk < 2; ++blk) {
;                 f32x4 y = (f32x4){0.f, 0.f, 0.f, 0.f};
; #pragma unroll
;                 for (int kk = 0; kk < 4; ++kk) { const bf16x8 hf = *(const LAS bf16x8*)(hl + (16 * blk + l16) * HROW + kk * 64 + kg * 16);
;                     y = __builtin_amdgcn_mfma_f32_16x16x32_bf16(hf, cfr[kk], y, 0, 0, 0); }
;                 y = __builtin_amdgcn_mfma_f32_16x16x32_bf16(blk ? cb1 : cb0, dh, y, 0, 0, 0);
;                 y = __builtin_amdgcn_mfma_f32_16x16x32_bf16(blk ? cb1 : cb0, dl, y, 0, 0, 0);
;                 bf16_t* o = yp + ((size_t)(4 * blk) * SEQ + t0) * BR;
;                 const unsigned w01 = cvtpk_s(gelu_tanh(y[0]), gelu_tanh(y[1])), w23 = cvtpk_s(gelu_tanh(y[2]), gelu_tanh(y[3]));
;                 o[0] = (bf16_t)(w01 & 0xffffu); o[(size_t)BR] = (bf16_t)(w01 >> 16); o[(size_t)2 * BR] = (bf16_t)(w23 & 0xffffu); o[(size_t)3 * BR] = (bf16_t)(w23 >> 16);
;             }
	v_mfma_f32_16x16x32_bf16 v[206:209], v[116:119], v[72:75], 0
	s_waitcnt lgkmcnt(6)
	v_mfma_f32_16x16x32_bf16 v[206:209], v[120:123], v[76:79], v[206:209]
	s_waitcnt lgkmcnt(5)
	v_mfma_f32_16x16x32_bf16 v[206:209], v[176:179], v[88:91], v[206:209]
	s_waitcnt lgkmcnt(4)
	v_mfma_f32_16x16x32_bf16 v[206:209], v[180:183], v[92:95], v[206:209]
	v_mfma_f32_16x16x32_bf16 v[206:209], v[108:111], v[96:99], v[206:209]
	v_mfma_f32_16x16x32_bf16 v[206:209], v[108:111], v[100:103], v[206:209]
	s_waitcnt lgkmcnt(3)
	v_mfma_f32_16x16x32_bf16 v[210:213], v[190:193], v[72:75], 0
	s_waitcnt lgkmcnt(2)
	v_mfma_f32_16x16x32_bf16 v[210:213], v[194:197], v[76:79], v[210:213]
	s_waitcnt lgkmcnt(1)
	v_mfma_f32_16x16x32_bf16 v[210:213], v[198:201], v[88:91], v[210:213]
	s_waitcnt lgkmcnt(0)
	v_mfma_f32_16x16x32_bf16 v[210:213], v[202:205], v[92:95], v[210:213]
	v_mfma_f32_16x16x32_bf16 v[210:213], v[112:115], v[96:99], v[210:213]
	v_mfma_f32_16x16x32_bf16 v[210:213], v[112:115], v[100:103], v[210:213]
	s_nop 1
	v_mul_f32_e32 v216, 0x3d372713, v206
	v_mul_f32_e32 v217, 0x3d372713, v207
	v_mul_f32_e32 v218, 0x3d372713, v208
	v_mul_f32_e32 v219, 0x3d372713, v209
	v_mul_f32_e32 v216, v206, v216
	v_mul_f32_e32 v217, v207, v217
	v_mul_f32_e32 v218, v208, v218
	v_mul_f32_e32 v219, v209, v219
	v_fma_f32 v216, v206, v216, v206
	v_fma_f32 v217, v207, v217, v207
	v_fma_f32 v218, v208, v218, v208
	v_fma_f32 v219, v209, v219, v209
	v_mul_f32_e32 v216, 0xc0135761, v216
	v_mul_f32_e32 v217, 0xc0135761, v217
	v_mul_f32_e32 v218, 0xc0135761, v218
	v_mul_f32_e32 v219, 0xc0135761, v219
	v_exp_f32_e32 v216, v216
	v_exp_f32_e32 v217, v217
	v_exp_f32_e32 v218, v218
	v_exp_f32_e32 v219, v219
	v_add_f32_e32 v216, 1.0, v216
	v_add_f32_e32 v217, 1.0, v217
	v_add_f32_e32 v218, 1.0, v218
	v_add_f32_e32 v219, 1.0, v219
	v_rcp_f32_e32 v216, v216
	v_rcp_f32_e32 v217, v217
	v_rcp_f32_e32 v218, v218
	v_rcp_f32_e32 v219, v219
	v_mul_f32_e32 v216, v206, v216
	v_mul_f32_e32 v217, v207, v217
	v_mul_f32_e32 v218, v208, v218
	v_mul_f32_e32 v219, v209, v219
	v_cvt_pk_bf16_f32 v220, v216, v217
	v_cvt_pk_bf16_f32 v221, v218, v219
	s_nop 0
	v_cndmask_b32_e64 v217, v220, v221, s[84:85]
	v_cndmask_b32_e64 v216, v221, v220, s[84:85]
	s_nop 0
	v_mov_b32_dpp v218, v217 quad_perm:[1,0,3,2] row_mask:0xf bank_mask:0xf
	v_perm_b32 v219, v218, v216, v231
	v_perm_b32 v222, v218, v216, v232
	global_store_dword v224, v219, s[78:79] offset:-4096
	global_store_dword v224, v222, s[78:79]
	ds_read_b128 v[108:111], v187
	ds_read_b128 v[112:115], v187 offset:64
	v_mul_f32_e32 v216, 0x3d372713, v210
	v_mul_f32_e32 v217, 0x3d372713, v211
	v_mul_f32_e32 v218, 0x3d372713, v212
	v_mul_f32_e32 v219, 0x3d372713, v213
	v_mul_f32_e32 v216, v210, v216
	v_mul_f32_e32 v217, v211, v217
	v_mul_f32_e32 v218, v212, v218
	v_mul_f32_e32 v219, v213, v219
	v_fma_f32 v216, v210, v216, v210
	v_fma_f32 v217, v211, v217, v211
	v_fma_f32 v218, v212, v218, v212
	v_fma_f32 v219, v213, v219, v213
	v_mul_f32_e32 v216, 0xc0135761, v216
	v_mul_f32_e32 v217, 0xc0135761, v217
	v_mul_f32_e32 v218, 0xc0135761, v218
	v_mul_f32_e32 v219, 0xc0135761, v219
	v_exp_f32_e32 v216, v216
	v_exp_f32_e32 v217, v217
	v_exp_f32_e32 v218, v218
	v_exp_f32_e32 v219, v219
	v_add_f32_e32 v216, 1.0, v216
	v_add_f32_e32 v217, 1.0, v217
	v_add_f32_e32 v218, 1.0, v218
	v_add_f32_e32 v219, 1.0, v219
	v_rcp_f32_e32 v216, v216
	v_rcp_f32_e32 v217, v217
	v_rcp_f32_e32 v218, v218
	v_rcp_f32_e32 v219, v219
	v_mul_f32_e32 v216, v210, v216
	v_mul_f32_e32 v217, v211, v217
	v_mul_f32_e32 v218, v212, v218
	v_mul_f32_e32 v219, v213, v219
	v_cvt_pk_bf16_f32 v220, v216, v217
	v_cvt_pk_bf16_f32 v221, v218, v219
	s_nop 0
	v_cndmask_b32_e64 v217, v220, v221, s[84:85]
	v_cndmask_b32_e64 v216, v221, v220, s[84:85]
	s_nop 0
	v_mov_b32_dpp v218, v217 quad_perm:[1,0,3,2] row_mask:0xf bank_mask:0xf
	v_perm_b32 v219, v218, v216, v231
	v_perm_b32 v222, v218, v216, v232
	global_store_dword v224, v219, s[80:81] offset:-4096
	global_store_dword v224, v222, s[80:81]
	v_add_u32_e32 v224, 0x10000, v224
	s_waitcnt lgkmcnt(0)
	global_load_lds_dwordx4 v[188:189], off
	v_lshl_add_u64 v[188:189], v[188:189], 0, s[76:77]
	s_add_i32 s75, s75, -1
	s_cmp_lg_u32 s75, 0
	s_cbranch_scc1 .Ls5b_step
	s_branch .LBB0_418
